# p5hoist: rwkv_post loads its loop-invariant ln/mu vectors once and issues all five per-trip loads at the top of the trip (one exposed latency per trip instead of two)
# speedup vs baseline: 1.0158x; 1.0090x over previous
.LBB0_876:
	s_cmp_lt_i32 s92, 6
	s_cselect_b64 s[4:5], -1, 0
	s_and_b64 s[0:1], s[4:5], s[2:3]
	s_andn2_b64 vcc, exec, s[0:1]
	s_cbranch_vccnz .LBB0_883
	v_lshrrev_b32_e32 v0, 4, v170
	v_and_b32_e32 v1, 60, v0
	v_lshl_add_u32 v18, s69, 5, v1
	s_mov_b32 s0, 0x40000
	v_cmp_gt_i32_e32 vcc, s0, v18
	s_and_saveexec_b64 s[6:7], vcc
	s_cbranch_execz .LBB0_882
	s_add_u32 s8, s66, 0x1d000000
	s_addc_u32 s9, s67, 0
	s_add_u32 s10, s66, 0x1f000000
	s_addc_u32 s11, s67, 0
	s_add_u32 s12, s64, 0x5200000
	v_and_b32_e32 v19, 3, v0
	v_lshlrev_b32_e32 v0, 2, v170
	s_addc_u32 s13, s65, 0
	v_and_b32_e32 v20, 60, v0
	s_lshl_b32 s18, s96, 5
	s_mov_b64 s[14:15], 0
	v_mov_b32_e32 v1, 0
	s_movk_i32 s19, 0x3000
	v_mov_b64_e32 v[2:3], s[66:67]
	s_mov_b64 s[16:17], 0xd002420
	v_mov_b32_e32 v21, 0x3a27c5ac
	s_mov_b32 s20, 0x800000
	s_movk_i32 s21, 0x2000
	s_mov_b32 s22, 0x3ffff
	v_and_or_b32 v22, v18, 12, v19
	v_lshl_or_b32 v23, v22, 6, v20
	v_lshlrev_b32_e32 v34, 2, v23
	v_mov_b32_e32 v35, v1
	v_readlane_b32 s40, v235, 27
	v_readlane_b32 s41, v235, 28
	v_readlane_b32 s42, v235, 45
	v_readlane_b32 s43, v235, 46
	v_readlane_b32 s44, v235, 47
	v_readlane_b32 s45, v235, 48
	s_nop 4
	global_load_dwordx4 v[150:153], v34, s[42:43]
	global_load_dwordx4 v[154:157], v34, s[44:45]
	v_lshl_add_u64 v[36:37], s[40:41], 0, v[34:35]
	v_add_co_u32_e32 v34, vcc, s21, v36
	s_nop 1
	v_addc_co_u32_e32 v35, vcc, 0, v37, vcc
	global_load_dwordx4 v[158:161], v[34:35], off
	s_branch .LBB0_880
.LBB0_879:
	v_readlane_b32 s36, v235, 23
	v_readlane_b32 s37, v235, 24
	v_readlane_b32 s38, v235, 25
	v_readlane_b32 s39, v235, 26
	v_readlane_b32 s40, v235, 27
	v_readlane_b32 s41, v235, 28
	v_readlane_b32 s42, v235, 29
	v_readlane_b32 s43, v235, 30
	v_readlane_b32 s44, v235, 31
	v_readlane_b32 s45, v235, 32
	v_readlane_b32 s46, v235, 33
	v_readlane_b32 s47, v235, 34
	v_readlane_b32 s48, v235, 35
	v_readlane_b32 s49, v235, 36
	v_readlane_b32 s50, v235, 37
	v_readlane_b32 s51, v235, 38
	v_readlane_b32 s36, v235, 39
	v_readlane_b32 s42, v235, 45
	v_readlane_b32 s43, v235, 46
	v_readlane_b32 s44, v235, 47
	v_readlane_b32 s45, v235, 48
	s_nop 0
	s_nop 2
	s_nop 0
	v_add_f32_e32 v23, v24, v25
	v_lshlrev_b64 v[4:5], 13, v[4:5]
	v_fmamk_f32 v23, v23, 0x3c800000, v21
	v_sub_co_u32_e32 v4, vcc, 0, v4
	v_mul_f32_e32 v40, 0x4b800000, v23
	s_nop 0
	v_subb_co_u32_e32 v5, vcc, 0, v5, vcc
	v_cmp_gt_f32_e64 s[2:3], s20, v23
	v_lshl_add_u64 v[4:5], v[6:7], 0, v[4:5]
	v_lshl_add_u64 v[4:5], v[4:5], 0, v[0:1]
	v_cndmask_b32_e64 v6, v23, v40, s[2:3]
	v_rsq_f32_e32 v0, v6
	s_waitcnt vmcnt(0)
	v_cndmask_b32_e64 v162, 0, v162, s[0:1]
	v_cndmask_b32_e64 v163, 0, v163, s[0:1]
	v_lshlrev_b32_e32 v24, 16, v12
	v_and_b32_e32 v25, 0xffff0000, v12
	v_lshlrev_b32_e32 v38, 16, v162
	v_mul_f32_e32 v6, 0x45800000, v0
	v_and_b32_e32 v39, 0xffff0000, v162
	v_lshlrev_b32_e32 v12, 16, v13
	v_and_b32_e32 v13, 0xffff0000, v13
	v_lshlrev_b32_e32 v14, 16, v163
	v_and_b32_e32 v15, 0xffff0000, v163
	v_cndmask_b32_e64 v0, v0, v6, s[2:3]
	v_pk_add_f32 v[38:39], v[38:39], v[24:25] neg_lo:[0,1] neg_hi:[0,1]
	v_pk_add_f32 v[14:15], v[14:15], v[12:13] neg_lo:[0,1] neg_hi:[0,1]
	v_pk_mul_f32 v[6:7], v[8:9], v[0:1] op_sel_hi:[1,0]
	v_pk_mul_f32 v[8:9], v[10:11], v[0:1] op_sel_hi:[1,0]
	v_add_u32_e32 v18, s18, v18
	v_cmp_lt_i32_e64 s[0:1], s22, v18
	v_add_co_u32_e32 v4, vcc, 0x9000000, v4
	s_or_b64 s[14:15], s[0:1], s[14:15]
	s_nop 0
	v_addc_co_u32_e32 v5, vcc, 0, v5, vcc
	v_readlane_b32 s37, v235, 40
	v_readlane_b32 s38, v235, 41
	v_readlane_b32 s39, v235, 42
	v_readlane_b32 s40, v235, 43
	v_readlane_b32 s41, v235, 44
	v_readlane_b32 s46, v235, 49
	v_readlane_b32 s47, v235, 50
	v_readlane_b32 s48, v235, 51
	v_readlane_b32 s49, v235, 52
	v_readlane_b32 s50, v235, 53
	v_readlane_b32 s51, v235, 54
	s_waitcnt vmcnt(4)
	v_lshlrev_b32_e32 v10, 16, v142
	v_and_b32_e32 v11, 0xffff0000, v142
	v_lshlrev_b32_e32 v16, 16, v143
	v_and_b32_e32 v17, 0xffff0000, v143
	s_waitcnt vmcnt(2)
	v_pk_fma_f32 v[6:7], v[6:7], v[150:151], v[154:155]
	v_pk_fma_f32 v[8:9], v[8:9], v[152:153], v[156:157]
	s_waitcnt vmcnt(1)
	v_pk_fma_f32 v[24:25], v[158:159], v[38:39], v[24:25]
	v_pk_fma_f32 v[12:13], v[14:15], v[160:161], v[12:13]
	s_waitcnt vmcnt(0)
	v_pk_fma_f32 v[6:7], v[148:149], v[24:25], v[6:7] op_sel_hi:[0,1,1]
	v_pk_fma_f32 v[8:9], v[148:149], v[12:13], v[8:9] op_sel_hi:[0,1,1]
	v_pk_mul_f32 v[6:7], v[6:7], v[10:11]
	v_pk_mul_f32 v[8:9], v[8:9], v[16:17]
	v_cvt_pk_bf16_f32 v6, v6, v7
	v_cvt_pk_bf16_f32 v7, v8, v9
	global_store_dwordx2 v[4:5], v[6:7], off offset:2048
	s_andn2_b64 exec, exec, s[14:15]
	s_cbranch_execz .LBB0_882
.LBB0_880:
	v_ashrrev_i32_e32 v4, 4, v18
	v_and_or_b32 v22, v18, 12, v19
	v_ashrrev_i32_e32 v5, 31, v4
	v_lshl_or_b32 v23, v22, 6, v20
	v_lshlrev_b64 v[6:7], 11, v[4:5]
	v_lshl_add_u64 v[6:7], s[12:13], 0, v[6:7]
	v_lshlrev_b32_e32 v0, 1, v23
	v_lshl_add_u64 v[6:7], v[6:7], 0, v[0:1]
	global_load_dwordx2 v[8:9], v[6:7], off nt
	v_mad_i64_i32 v[6:7], s[0:1], v4, s19, v[2:3]
	v_lshl_add_u64 v[16:17], v[6:7], 0, v[0:1]
	v_add_co_u32_e32 v10, vcc, 0xd002000, v16
	v_mov_b32_e32 v14, v1
	s_nop 0
	v_addc_co_u32_e32 v11, vcc, 0, v17, vcc
	global_load_dwordx2 v[12:13], v[10:11], off offset:1056
	v_lshl_add_u64 v[140:141], v[16:17], 0, s[16:17]
	v_add_co_u32_e32 v140, vcc, 0xffffd000, v140
	s_nop 1
	v_addc_co_u32_e32 v141, vcc, -1, v141, vcc
	global_load_dwordx2 v[162:163], v[140:141], off
	v_lshlrev_b64 v[140:141], 10, v[4:5]
	v_lshl_add_u64 v[140:141], v[140:141], 1, s[8:9]
	v_lshl_add_u64 v[140:141], v[140:141], 0, v[0:1]
	global_load_dwordx2 v[142:143], v[140:141], off nt
	v_lshlrev_b64 v[144:145], 6, v[4:5]
	v_lshl_add_u64 v[144:145], s[10:11], 0, v[144:145]
	v_lshlrev_b32_e32 v146, 2, v22
	v_mov_b32_e32 v147, v1
	v_lshl_add_u64 v[144:145], v[144:145], 0, v[146:147]
	global_load_dword v148, v[144:145], off
	v_and_b32_e32 v10, 0xfff0, v18
	v_cmp_ne_u32_e32 vcc, 0, v10
	s_waitcnt vmcnt(4)
	v_lshlrev_b32_e32 v10, 16, v9
	v_and_b32_e32 v11, 0xffff0000, v9
	v_lshlrev_b32_e32 v24, 16, v8
	v_and_b32_e32 v25, 0xffff0000, v8
	v_mov_b32_e32 v8, v24
	v_mov_b32_e32 v9, v10
	v_mov_b32_e32 v26, v25
	v_mov_b32_e32 v27, v11
	v_pk_add_f32 v[8:9], v[8:9], v[26:27]
	s_nop 0
	v_add_f32_e32 v8, v8, v9
	s_nop 1
	v_add_f32_dpp v8, v8, v8 quad_perm:[1,0,3,2] row_mask:0xf bank_mask:0xf bound_ctrl:1
	s_nop 1
	v_add_f32_dpp v8, v8, v8 quad_perm:[2,3,0,1] row_mask:0xf bank_mask:0xf bound_ctrl:1
	s_nop 1
	v_add_f32_dpp v8, v8, v8 row_half_mirror row_mask:0xf bank_mask:0xf bound_ctrl:1
	s_nop 1
	v_add_f32_dpp v8, v8, v8 row_mirror row_mask:0xf bank_mask:0xf bound_ctrl:1
	v_mul_f32_e32 v26, 0x3c800000, v8
	v_pk_add_f32 v[8:9], v[24:25], v[26:27] op_sel_hi:[1,0] neg_lo:[0,1] neg_hi:[0,1]
	v_pk_add_f32 v[10:11], v[10:11], v[26:27] op_sel_hi:[1,0] neg_lo:[0,1] neg_hi:[0,1]
	v_pk_mul_f32 v[24:25], v[8:9], v[8:9]
	v_pk_mul_f32 v[26:27], v[10:11], v[10:11]
	v_add_f32_e32 v15, v24, v25
	v_add_f32_e32 v15, v26, v15
	v_add_f32_e32 v15, v27, v15
	s_nop 1
	v_add_f32_dpp v15, v15, v15 quad_perm:[1,0,3,2] row_mask:0xf bank_mask:0xf bound_ctrl:1
	s_nop 1
	v_add_f32_dpp v15, v15, v15 quad_perm:[2,3,0,1] row_mask:0xf bank_mask:0xf bound_ctrl:1
	s_nop 1
	v_add_f32_dpp v24, v15, v15 row_half_mirror row_mask:0xf bank_mask:0xf bound_ctrl:1
	v_mov_b32_e32 v15, v1
	s_nop 0
	v_mov_b32_dpp v25, v24 row_mirror row_mask:0xf bank_mask:0xf bound_ctrl:1
	s_mov_b64 s[0:1], vcc
	s_branch .LBB0_879
